# SwiGLU epilogue hand-written: packed f32 mul/add, exp/rcp interleaved over 8 elements (no dependent-chain stalls), 32-bit offset addressing
# speedup vs baseline: 1.0118x; 1.0023x over previous
; DI unsigned cvt_pk_bf16(float lo, float hi) { unsigned r; asm volatile("v_cvt_pk_bf16_f32 %0, %1, %2" : "=v"(r) : "v"(lo), "v"(hi)); return r; }
; DI float siluf_(float x) { return x * __builtin_amdgcn_rcpf(1.0f + __expf(-x)); }
;     DI void operator()(const f32x4 (&acc)[2][2][4][2], const pg8::Unit& u, int wr, int wc, int fr, int fq) const {
;         const int row0 = u.pm * 256 + wr * 64 + fr, col0 = u.pn * 128 + wc * 32 + 8 * fq;
; #pragma unroll
;         for (int ai = 0; ai < 2; ++ai)
; #pragma unroll
;             for (int m = 0; m < 4; ++m) {
;                 bf16_t* rowp = H + (size_t)(row0 + ai * 128 + m * 16) * FF_ + col0;
;                 float h[8];
; #pragma unroll
;                 for (int n = 0; n < 2; ++n)
; #pragma unroll
;                     for (int j = 0; j < 4; ++j) { const float gg = acc[ai][0][m][n][j], uu = acc[ai][1][m][n][j]; h[n * 4 + j] = siluf_(gg) * uu; }
;                 u32x4 w; w.x = cvt_pk_bf16(h[0], h[1]); w.y = cvt_pk_bf16(h[2], h[3]); w.z = cvt_pk_bf16(h[4], h[5]); w.w = cvt_pk_bf16(h[6], h[7]);
;                 *(u32x4*)rowp = w;
;             }
.LBB0_773:
	v_mov_b32_e32 v128, v163
	s_lshl_b32 s7, s34, 8
	s_add_i32 s7, s7, s55
	v_and_or_b32 v136, v128, 15, s7
	v_lshrrev_b32_e32 v128, 1, v128
	v_and_b32_e32 v128, 0x78, v128
	v_lshl_or_b32 v138, s26, 7, v128
	v_readlane_b32 s96, v255, 42
	s_andn2_b64 vcc, exec, s[2:3]
	v_readlane_b32 s97, v255, 43
	v_mul_u32_u24_e32 v144, 0x1600, v136
	v_lshl_add_u32 v144, v138, 1, v144
	v_mov_b32_e32 v244, 0xbfb8aa3b
	v_mov_b32_e32 v245, 0xbfb8aa3b
	v_mov_b32_e32 v246, 1.0
	v_mov_b32_e32 v247, 1.0
	v_pk_mul_f32 v[228:229], v[124:125], v[244:245]
	v_pk_mul_f32 v[230:231], v[126:127], v[244:245]
	v_pk_mul_f32 v[232:233], v[116:117], v[244:245]
	v_pk_mul_f32 v[234:235], v[118:119], v[244:245]
	v_exp_f32_e32 v228, v228
	v_exp_f32_e32 v229, v229
	v_exp_f32_e32 v230, v230
	v_exp_f32_e32 v231, v231
	v_exp_f32_e32 v232, v232
	v_exp_f32_e32 v233, v233
	v_exp_f32_e32 v234, v234
	v_exp_f32_e32 v235, v235
	v_pk_add_f32 v[228:229], v[246:247], v[228:229]
	v_pk_add_f32 v[230:231], v[246:247], v[230:231]
	v_pk_add_f32 v[232:233], v[246:247], v[232:233]
	v_pk_add_f32 v[234:235], v[246:247], v[234:235]
	v_rcp_f32_e32 v228, v228
	v_rcp_f32_e32 v229, v229
	v_rcp_f32_e32 v230, v230
	v_rcp_f32_e32 v231, v231
	v_rcp_f32_e32 v232, v232
	v_rcp_f32_e32 v233, v233
	v_rcp_f32_e32 v234, v234
	v_rcp_f32_e32 v235, v235
	v_pk_mul_f32 v[228:229], v[124:125], v[228:229]
	v_pk_mul_f32 v[230:231], v[126:127], v[230:231]
	v_pk_mul_f32 v[232:233], v[116:117], v[232:233]
	v_pk_mul_f32 v[234:235], v[118:119], v[234:235]
	v_pk_mul_f32 v[228:229], v[228:229], v[120:121]
	v_pk_mul_f32 v[230:231], v[230:231], v[122:123]
	v_pk_mul_f32 v[232:233], v[232:233], v[112:113]
	v_pk_mul_f32 v[234:235], v[234:235], v[114:115]
	v_mov_b32_e32 v145, v144
	v_cvt_pk_bf16_f32 v124, v228, v229
	v_cvt_pk_bf16_f32 v125, v230, v231
	v_cvt_pk_bf16_f32 v126, v232, v233
	v_cvt_pk_bf16_f32 v127, v234, v235
	global_store_dwordx4 v145, v[124:127], s[20:21]
	v_pk_mul_f32 v[236:237], v[108:109], v[244:245]
	v_pk_mul_f32 v[238:239], v[110:111], v[244:245]
	v_pk_mul_f32 v[240:241], v[100:101], v[244:245]
	v_pk_mul_f32 v[242:243], v[102:103], v[244:245]
	v_exp_f32_e32 v236, v236
	v_exp_f32_e32 v237, v237
	v_exp_f32_e32 v238, v238
	v_exp_f32_e32 v239, v239
	v_exp_f32_e32 v240, v240
	v_exp_f32_e32 v241, v241
	v_exp_f32_e32 v242, v242
	v_exp_f32_e32 v243, v243
	v_pk_add_f32 v[236:237], v[246:247], v[236:237]
	v_pk_add_f32 v[238:239], v[246:247], v[238:239]
	v_pk_add_f32 v[240:241], v[246:247], v[240:241]
	v_pk_add_f32 v[242:243], v[246:247], v[242:243]
	v_rcp_f32_e32 v236, v236
	v_rcp_f32_e32 v237, v237
	v_rcp_f32_e32 v238, v238
	v_rcp_f32_e32 v239, v239
	v_rcp_f32_e32 v240, v240
	v_rcp_f32_e32 v241, v241
	v_rcp_f32_e32 v242, v242
	v_rcp_f32_e32 v243, v243
	v_pk_mul_f32 v[236:237], v[108:109], v[236:237]
	v_pk_mul_f32 v[238:239], v[110:111], v[238:239]
	v_pk_mul_f32 v[240:241], v[100:101], v[240:241]
	v_pk_mul_f32 v[242:243], v[102:103], v[242:243]
	v_pk_mul_f32 v[236:237], v[236:237], v[104:105]
	v_pk_mul_f32 v[238:239], v[238:239], v[106:107]
	v_pk_mul_f32 v[240:241], v[240:241], v[96:97]
	v_pk_mul_f32 v[242:243], v[242:243], v[98:99]
	v_add_u32_e32 v146, 0x16000, v144
	v_cvt_pk_bf16_f32 v108, v236, v237
	v_cvt_pk_bf16_f32 v109, v238, v239
	v_cvt_pk_bf16_f32 v110, v240, v241
	v_cvt_pk_bf16_f32 v111, v242, v243
	global_store_dwordx4 v146, v[108:111], s[20:21]
	v_pk_mul_f32 v[228:229], v[92:93], v[244:245]
	v_pk_mul_f32 v[230:231], v[94:95], v[244:245]
	v_pk_mul_f32 v[232:233], v[84:85], v[244:245]
	v_pk_mul_f32 v[234:235], v[86:87], v[244:245]
	v_exp_f32_e32 v228, v228
	v_exp_f32_e32 v229, v229
	v_exp_f32_e32 v230, v230
	v_exp_f32_e32 v231, v231
	v_exp_f32_e32 v232, v232
	v_exp_f32_e32 v233, v233
	v_exp_f32_e32 v234, v234
	v_exp_f32_e32 v235, v235
	v_pk_add_f32 v[228:229], v[246:247], v[228:229]
	v_pk_add_f32 v[230:231], v[246:247], v[230:231]
	v_pk_add_f32 v[232:233], v[246:247], v[232:233]
	v_pk_add_f32 v[234:235], v[246:247], v[234:235]
	v_rcp_f32_e32 v228, v228
	v_rcp_f32_e32 v229, v229
	v_rcp_f32_e32 v230, v230
	v_rcp_f32_e32 v231, v231
	v_rcp_f32_e32 v232, v232
	v_rcp_f32_e32 v233, v233
	v_rcp_f32_e32 v234, v234
	v_rcp_f32_e32 v235, v235
	v_pk_mul_f32 v[228:229], v[92:93], v[228:229]
	v_pk_mul_f32 v[230:231], v[94:95], v[230:231]
	v_pk_mul_f32 v[232:233], v[84:85], v[232:233]
	v_pk_mul_f32 v[234:235], v[86:87], v[234:235]
	v_pk_mul_f32 v[228:229], v[228:229], v[88:89]
	v_pk_mul_f32 v[230:231], v[230:231], v[90:91]
	v_pk_mul_f32 v[232:233], v[232:233], v[80:81]
	v_pk_mul_f32 v[234:235], v[234:235], v[82:83]
	v_add_u32_e32 v145, 0x2c000, v144
	v_cvt_pk_bf16_f32 v92, v228, v229
	v_cvt_pk_bf16_f32 v93, v230, v231
	v_cvt_pk_bf16_f32 v94, v232, v233
	v_cvt_pk_bf16_f32 v95, v234, v235
	global_store_dwordx4 v145, v[92:95], s[20:21]
	v_pk_mul_f32 v[236:237], v[76:77], v[244:245]
	v_pk_mul_f32 v[238:239], v[78:79], v[244:245]
	v_pk_mul_f32 v[240:241], v[68:69], v[244:245]
	v_pk_mul_f32 v[242:243], v[70:71], v[244:245]
	v_exp_f32_e32 v236, v236
	v_exp_f32_e32 v237, v237
	v_exp_f32_e32 v238, v238
	v_exp_f32_e32 v239, v239
	v_exp_f32_e32 v240, v240
	v_exp_f32_e32 v241, v241
	v_exp_f32_e32 v242, v242
	v_exp_f32_e32 v243, v243
	v_pk_add_f32 v[236:237], v[246:247], v[236:237]
	v_pk_add_f32 v[238:239], v[246:247], v[238:239]
	v_pk_add_f32 v[240:241], v[246:247], v[240:241]
	v_pk_add_f32 v[242:243], v[246:247], v[242:243]
	v_rcp_f32_e32 v236, v236
	v_rcp_f32_e32 v237, v237
	v_rcp_f32_e32 v238, v238
	v_rcp_f32_e32 v239, v239
	v_rcp_f32_e32 v240, v240
	v_rcp_f32_e32 v241, v241
	v_rcp_f32_e32 v242, v242
	v_rcp_f32_e32 v243, v243
	v_pk_mul_f32 v[236:237], v[76:77], v[236:237]
	v_pk_mul_f32 v[238:239], v[78:79], v[238:239]
; DI unsigned cvt_pk_bf16(float lo, float hi) { unsigned r; asm volatile("v_cvt_pk_bf16_f32 %0, %1, %2" : "=v"(r) : "v"(lo), "v"(hi)); return r; }
; DI float siluf_(float x) { return x * __builtin_amdgcn_rcpf(1.0f + __expf(-x)); }
;     DI void operator()(const f32x4 (&acc)[2][2][4][2], const pg8::Unit& u, int wr, int wc, int fr, int fq) const {
;         const int row0 = u.pm * 256 + wr * 64 + fr, col0 = u.pn * 128 + wc * 32 + 8 * fq;
; #pragma unroll
;         for (int ai = 0; ai < 2; ++ai)
; #pragma unroll
;             for (int m = 0; m < 4; ++m) {
;                 bf16_t* rowp = H + (size_t)(row0 + ai * 128 + m * 16) * FF_ + col0;
;                 float h[8];
; #pragma unroll
;                 for (int n = 0; n < 2; ++n)
; #pragma unroll
;                     for (int j = 0; j < 4; ++j) { const float gg = acc[ai][0][m][n][j], uu = acc[ai][1][m][n][j]; h[n * 4 + j] = siluf_(gg) * uu; }
;                 u32x4 w; w.x = cvt_pk_bf16(h[0], h[1]); w.y = cvt_pk_bf16(h[2], h[3]); w.z = cvt_pk_bf16(h[4], h[5]); w.w = cvt_pk_bf16(h[6], h[7]);
;                 *(u32x4*)rowp = w;
;             }
	v_pk_mul_f32 v[240:241], v[68:69], v[240:241]
	v_pk_mul_f32 v[242:243], v[70:71], v[242:243]
	v_pk_mul_f32 v[236:237], v[236:237], v[72:73]
	v_pk_mul_f32 v[238:239], v[238:239], v[74:75]
	v_pk_mul_f32 v[240:241], v[240:241], v[64:65]
	v_pk_mul_f32 v[242:243], v[242:243], v[66:67]
	v_add_u32_e32 v146, 0x42000, v144
	v_cvt_pk_bf16_f32 v76, v236, v237
	v_cvt_pk_bf16_f32 v77, v238, v239
	v_cvt_pk_bf16_f32 v78, v240, v241
	v_cvt_pk_bf16_f32 v79, v242, v243
	global_store_dwordx4 v146, v[76:79], s[20:21]
	v_pk_mul_f32 v[228:229], v[60:61], v[244:245]
	v_pk_mul_f32 v[230:231], v[62:63], v[244:245]
	v_pk_mul_f32 v[232:233], v[52:53], v[244:245]
	v_pk_mul_f32 v[234:235], v[54:55], v[244:245]
	v_exp_f32_e32 v228, v228
	v_exp_f32_e32 v229, v229
	v_exp_f32_e32 v230, v230
	v_exp_f32_e32 v231, v231
	v_exp_f32_e32 v232, v232
	v_exp_f32_e32 v233, v233
	v_exp_f32_e32 v234, v234
	v_exp_f32_e32 v235, v235
	v_pk_add_f32 v[228:229], v[246:247], v[228:229]
	v_pk_add_f32 v[230:231], v[246:247], v[230:231]
	v_pk_add_f32 v[232:233], v[246:247], v[232:233]
	v_pk_add_f32 v[234:235], v[246:247], v[234:235]
	v_rcp_f32_e32 v228, v228
	v_rcp_f32_e32 v229, v229
	v_rcp_f32_e32 v230, v230
	v_rcp_f32_e32 v231, v231
	v_rcp_f32_e32 v232, v232
	v_rcp_f32_e32 v233, v233
	v_rcp_f32_e32 v234, v234
	v_rcp_f32_e32 v235, v235
	v_pk_mul_f32 v[228:229], v[60:61], v[228:229]
	v_pk_mul_f32 v[230:231], v[62:63], v[230:231]
	v_pk_mul_f32 v[232:233], v[52:53], v[232:233]
	v_pk_mul_f32 v[234:235], v[54:55], v[234:235]
	v_pk_mul_f32 v[228:229], v[228:229], v[56:57]
	v_pk_mul_f32 v[230:231], v[230:231], v[58:59]
	v_pk_mul_f32 v[232:233], v[232:233], v[48:49]
	v_pk_mul_f32 v[234:235], v[234:235], v[50:51]
	v_add_u32_e32 v145, 0xb0000, v144
	v_cvt_pk_bf16_f32 v60, v228, v229
	v_cvt_pk_bf16_f32 v61, v230, v231
	v_cvt_pk_bf16_f32 v62, v232, v233
	v_cvt_pk_bf16_f32 v63, v234, v235
	global_store_dwordx4 v145, v[60:63], s[20:21]
	v_pk_mul_f32 v[236:237], v[44:45], v[244:245]
	v_pk_mul_f32 v[238:239], v[46:47], v[244:245]
	v_pk_mul_f32 v[240:241], v[36:37], v[244:245]
	v_pk_mul_f32 v[242:243], v[38:39], v[244:245]
	v_exp_f32_e32 v236, v236
	v_exp_f32_e32 v237, v237
	v_exp_f32_e32 v238, v238
	v_exp_f32_e32 v239, v239
	v_exp_f32_e32 v240, v240
	v_exp_f32_e32 v241, v241
	v_exp_f32_e32 v242, v242
	v_exp_f32_e32 v243, v243
	v_pk_add_f32 v[236:237], v[246:247], v[236:237]
	v_pk_add_f32 v[238:239], v[246:247], v[238:239]
	v_pk_add_f32 v[240:241], v[246:247], v[240:241]
	v_pk_add_f32 v[242:243], v[246:247], v[242:243]
	v_rcp_f32_e32 v236, v236
	v_rcp_f32_e32 v237, v237
	v_rcp_f32_e32 v238, v238
	v_rcp_f32_e32 v239, v239
	v_rcp_f32_e32 v240, v240
	v_rcp_f32_e32 v241, v241
	v_rcp_f32_e32 v242, v242
	v_rcp_f32_e32 v243, v243
	v_pk_mul_f32 v[236:237], v[44:45], v[236:237]
	v_pk_mul_f32 v[238:239], v[46:47], v[238:239]
	v_pk_mul_f32 v[240:241], v[36:37], v[240:241]
	v_pk_mul_f32 v[242:243], v[38:39], v[242:243]
	v_pk_mul_f32 v[236:237], v[236:237], v[40:41]
	v_pk_mul_f32 v[238:239], v[238:239], v[42:43]
	v_pk_mul_f32 v[240:241], v[240:241], v[32:33]
	v_pk_mul_f32 v[242:243], v[242:243], v[34:35]
	v_add_u32_e32 v146, 0xc6000, v144
	v_cvt_pk_bf16_f32 v44, v236, v237
	v_cvt_pk_bf16_f32 v45, v238, v239
	v_cvt_pk_bf16_f32 v46, v240, v241
	v_cvt_pk_bf16_f32 v47, v242, v243
	global_store_dwordx4 v146, v[44:47], s[20:21]
	v_pk_mul_f32 v[228:229], v[28:29], v[244:245]
	v_pk_mul_f32 v[230:231], v[30:31], v[244:245]
	v_pk_mul_f32 v[232:233], v[20:21], v[244:245]
	v_pk_mul_f32 v[234:235], v[22:23], v[244:245]
	v_exp_f32_e32 v228, v228
	v_exp_f32_e32 v229, v229
	v_exp_f32_e32 v230, v230
	v_exp_f32_e32 v231, v231
	v_exp_f32_e32 v232, v232
	v_exp_f32_e32 v233, v233
	v_exp_f32_e32 v234, v234
	v_exp_f32_e32 v235, v235
	v_pk_add_f32 v[228:229], v[246:247], v[228:229]
	v_pk_add_f32 v[230:231], v[246:247], v[230:231]
	v_pk_add_f32 v[232:233], v[246:247], v[232:233]
	v_pk_add_f32 v[234:235], v[246:247], v[234:235]
	v_rcp_f32_e32 v228, v228
	v_rcp_f32_e32 v229, v229
	v_rcp_f32_e32 v230, v230
	v_rcp_f32_e32 v231, v231
	v_rcp_f32_e32 v232, v232
	v_rcp_f32_e32 v233, v233
	v_rcp_f32_e32 v234, v234
	v_rcp_f32_e32 v235, v235
	v_pk_mul_f32 v[228:229], v[28:29], v[228:229]
	v_pk_mul_f32 v[230:231], v[30:31], v[230:231]
	v_pk_mul_f32 v[232:233], v[20:21], v[232:233]
	v_pk_mul_f32 v[234:235], v[22:23], v[234:235]
	v_pk_mul_f32 v[228:229], v[228:229], v[24:25]
	v_pk_mul_f32 v[230:231], v[230:231], v[26:27]
	v_pk_mul_f32 v[232:233], v[232:233], v[16:17]
	v_pk_mul_f32 v[234:235], v[234:235], v[18:19]
	v_add_u32_e32 v145, 0xdc000, v144
	v_cvt_pk_bf16_f32 v28, v228, v229
	v_cvt_pk_bf16_f32 v29, v230, v231
	v_cvt_pk_bf16_f32 v30, v232, v233
	v_cvt_pk_bf16_f32 v31, v234, v235
	global_store_dwordx4 v145, v[28:31], s[20:21]
	v_pk_mul_f32 v[236:237], v[12:13], v[244:245]
	v_pk_mul_f32 v[238:239], v[14:15], v[244:245]
	v_pk_mul_f32 v[240:241], v[4:5], v[244:245]
	v_pk_mul_f32 v[242:243], v[6:7], v[244:245]
	v_exp_f32_e32 v236, v236
	v_exp_f32_e32 v237, v237
	v_exp_f32_e32 v238, v238
	v_exp_f32_e32 v239, v239
	v_exp_f32_e32 v240, v240
	v_exp_f32_e32 v241, v241
	v_exp_f32_e32 v242, v242
	v_exp_f32_e32 v243, v243
	v_pk_add_f32 v[236:237], v[246:247], v[236:237]
	v_pk_add_f32 v[238:239], v[246:247], v[238:239]
	v_pk_add_f32 v[240:241], v[246:247], v[240:241]
	v_pk_add_f32 v[242:243], v[246:247], v[242:243]
	v_rcp_f32_e32 v236, v236
	v_rcp_f32_e32 v237, v237
	v_rcp_f32_e32 v238, v238
	v_rcp_f32_e32 v239, v239
	v_rcp_f32_e32 v240, v240
	v_rcp_f32_e32 v241, v241
	v_rcp_f32_e32 v242, v242
	v_rcp_f32_e32 v243, v243
	v_pk_mul_f32 v[236:237], v[12:13], v[236:237]
	v_pk_mul_f32 v[238:239], v[14:15], v[238:239]
	v_pk_mul_f32 v[240:241], v[4:5], v[240:241]
	v_pk_mul_f32 v[242:243], v[6:7], v[242:243]
	v_pk_mul_f32 v[236:237], v[236:237], v[8:9]
	v_pk_mul_f32 v[238:239], v[238:239], v[10:11]
	v_pk_mul_f32 v[240:241], v[240:241], v[0:1]
	v_pk_mul_f32 v[242:243], v[242:243], v[2:3]
	v_add_u32_e32 v146, 0xf2000, v144
	v_cvt_pk_bf16_f32 v12, v236, v237
	v_cvt_pk_bf16_f32 v13, v238, v239
	v_cvt_pk_bf16_f32 v14, v240, v241
	v_cvt_pk_bf16_f32 v15, v242, v243
	global_store_dwordx4 v146, v[12:15], s[20:21]
	s_mov_b64 s[14:15], -1
	s_cbranch_vccnz .LBB0_766
	s_andn2_b64 vcc, exec, s[0:1]
	s_cbranch_vccnz .LBB0_765
	s_barrier
	s_branch .LBB0_765
